# NA local tiles: QK^T MFMAs of the second query group issued between the scale/bias/mask VALU of the first, and P0*V MFMAs between the exp/sum VALU of the second (matrix pipe fed from inside the VALU s
# speedup vs baseline: 1.0012x; 1.0012x over previous
.LBB0_342:
	v_add_u32_e32 v50, v58, v141
	v_mov_b64_e32 v[60:61], s[26:27]
	s_movk_i32 s10, 0x1800
	v_mad_i64_i32 v[50:51], s[2:3], v50, s10, v[60:61]
	v_lshl_add_u64 v[50:51], v[50:51], 0, v[0:1]
	v_lshlrev_b32_e32 v62, 1, v124
	v_mov_b32_e32 v63, v1
	v_add_u32_e32 v58, v58, v143
	v_lshl_add_u64 v[50:51], v[50:51], 0, v[62:63]
	v_mad_i64_i32 v[58:59], s[2:3], v58, s10, v[60:61]
	v_add_co_u32_e32 v54, vcc, 0x1000, v50
	v_lshl_add_u64 v[58:59], v[58:59], 0, v[0:1]
	s_nop 0
	v_addc_co_u32_e32 v55, vcc, 0, v51, vcc
	v_lshl_add_u64 v[58:59], v[58:59], 0, v[62:63]
	v_add_co_u32_e32 v62, vcc, 0x1000, v58
	global_load_dwordx4 v[50:53], v[50:51], off offset:2048
	s_nop 0
	global_load_dwordx4 v[54:57], v[54:55], off
	v_addc_co_u32_e32 v63, vcc, 0, v59, vcc
	global_load_dwordx4 v[58:61], v[58:59], off offset:2048
	s_nop 0
	global_load_dwordx4 v[62:65], v[62:63], off
	s_and_b32 s15, s14, 64
	v_add_u32_e32 v66, s24, v148
	s_cmp_gt_u32 s24, 8
	s_cselect_b64 s[10:11], -1, 0
	s_cmp_lt_u32 s24, 9
	v_cmp_gt_u32_e32 vcc, 8, v66
	s_movk_i32 s13, 0x1800
	s_cselect_b64 s[28:29], -1, 0
	s_or_b64 s[2:3], s[10:11], vcc
	s_and_saveexec_b64 s[38:39], s[2:3]
	s_cbranch_execz .LBB0_337
	v_or_b32_e32 v66, s15, v138
	v_mad_u32_u24 v82, v66, s16, v145
	s_cmp_lt_u32 s24, 9
	s_cbranch_scc0 .Lna_ctx_tile
	s_bitcmp1_b32 s100, 6
	s_cbranch_scc1 .Lna_loc_h1
	ds_read_b128 v[164:167], v82 offset:0
	ds_read_b128 v[168:171], v82 offset:64
	ds_read_b128 v[172:175], v82 offset:2304
	ds_read_b128 v[176:179], v82 offset:2368
	ds_read_b128 v[180:183], v82 offset:4608
	ds_read_b128 v[184:187], v82 offset:4672
	ds_read2_b32 v[224:225], v147 offset0:16 offset1:17
	ds_read2_b32 v[226:227], v147 offset0:18 offset1:19
	ds_read2_b32 v[228:229], v147 offset0:32 offset1:33
	ds_read2_b32 v[230:231], v147 offset0:34 offset1:35
	v_mov_b32_e32 v158, 0xf149f2ca
	s_waitcnt lgkmcnt(9)
	v_mfma_f32_16x16x32_bf16 v[90:93], v[164:167], v[38:41], 0
	s_waitcnt lgkmcnt(8)
	v_mfma_f32_16x16x32_bf16 v[90:93], v[168:171], v[34:37], v[90:93]
	s_waitcnt lgkmcnt(7)
	v_mfma_f32_16x16x32_bf16 v[94:97], v[172:175], v[38:41], 0
	s_waitcnt lgkmcnt(6)
	v_mfma_f32_16x16x32_bf16 v[94:97], v[176:179], v[34:37], v[94:97]
	ds_read2_b32 v[232:233], v147 offset0:0 offset1:1
	ds_read2_b32 v[234:235], v147 offset0:2 offset1:3
	ds_read2_b32 v[236:237], v147 offset0:16 offset1:17
	ds_read2_b32 v[238:239], v147 offset0:18 offset1:19
	ds_read2_b32 v[240:241], v147 offset0:32 offset1:33
	ds_read2_b32 v[242:243], v147 offset0:34 offset1:35
	v_mfma_f32_16x16x32_bf16 v[98:101], v[164:167], v[46:49], 0
	v_or_b32_e32 v160, s15, v135
	v_mul_u32_u24_e32 v160, 0x48, v160
	v_lshl_add_u32 v160, v160, 1, v136
	s_waitcnt lgkmcnt(6)
	v_fmac_f32_e32 v224, 0x3e38aa3b, v90
	v_mfma_f32_16x16x32_bf16 v[98:101], v[168:171], v[42:45], v[98:101]
	v_fmac_f32_e32 v225, 0x3e38aa3b, v91
	v_fmac_f32_e32 v226, 0x3e38aa3b, v92
	v_fmac_f32_e32 v227, 0x3e38aa3b, v93
	v_fmac_f32_e32 v228, 0x3e38aa3b, v94
	v_mfma_f32_16x16x32_bf16 v[102:105], v[172:175], v[46:49], 0
	v_fmac_f32_e32 v229, 0x3e38aa3b, v95
	v_fmac_f32_e32 v230, 0x3e38aa3b, v96
	v_fmac_f32_e32 v231, 0x3e38aa3b, v97
	v_cndmask_b32_e64 v224, v158, v224, s[40:41]
	v_mfma_f32_16x16x32_bf16 v[102:105], v[176:179], v[42:45], v[102:105]
	v_cndmask_b32_e64 v225, v158, v225, s[42:43]
	v_cndmask_b32_e64 v226, v158, v226, s[44:45]
	v_cndmask_b32_e64 v227, v158, v227, s[46:47]
	v_cndmask_b32_e64 v228, v158, v228, s[48:49]
	v_mfma_f32_16x16x32_bf16 v[106:109], v[180:183], v[46:49], 0
	v_cndmask_b32_e64 v229, v158, v229, s[50:51]
	v_cndmask_b32_e64 v230, v158, v230, s[52:53]
	v_cndmask_b32_e64 v231, v158, v231, s[54:55]
	v_max3_f32 v150, v224, s18, v225
	v_mfma_f32_16x16x32_bf16 v[106:109], v[184:187], v[42:45], v[106:109]
	v_max3_f32 v150, v150, v226, v227
	v_max3_f32 v150, v150, v228, v229
	v_max3_f32 v150, v150, v230, v231
	s_waitcnt lgkmcnt(0)
	ds_read_b64_tr_b16 v[164:165], v160 offset:18432
	ds_read_b64_tr_b16 v[166:167], v160 offset:20736
	ds_read_b64_tr_b16 v[168:169], v160 offset:18464
	ds_read_b64_tr_b16 v[170:171], v160 offset:20768
	ds_read_b64_tr_b16 v[172:173], v160 offset:23040
	ds_read_b64_tr_b16 v[174:175], v160 offset:25344
	ds_read_b64_tr_b16 v[176:177], v160 offset:23072
	ds_read_b64_tr_b16 v[178:179], v160 offset:25376
	v_fmac_f32_e32 v232, 0x3e38aa3b, v98
	v_fmac_f32_e32 v233, 0x3e38aa3b, v99
	v_fmac_f32_e32 v234, 0x3e38aa3b, v100
	v_fmac_f32_e32 v235, 0x3e38aa3b, v101
	v_fmac_f32_e32 v236, 0x3e38aa3b, v102
	v_fmac_f32_e32 v237, 0x3e38aa3b, v103
	v_fmac_f32_e32 v238, 0x3e38aa3b, v104
	v_fmac_f32_e32 v239, 0x3e38aa3b, v105
	v_fmac_f32_e32 v240, 0x3e38aa3b, v106
	v_fmac_f32_e32 v241, 0x3e38aa3b, v107
	v_fmac_f32_e32 v242, 0x3e38aa3b, v108
	v_fmac_f32_e32 v243, 0x3e38aa3b, v109
	v_cndmask_b32_e64 v232, v158, v232, s[72:73]
	v_cndmask_b32_e64 v233, v158, v233, s[74:75]
	v_cndmask_b32_e64 v234, v158, v234, s[76:77]
	v_cndmask_b32_e64 v235, v158, v235, s[78:79]
	v_cndmask_b32_e64 v236, v158, v236, s[80:81]
	v_cndmask_b32_e64 v237, v158, v237, s[82:83]
	v_cndmask_b32_e64 v238, v158, v238, s[84:85]
	v_cndmask_b32_e64 v239, v158, v239, s[86:87]
	v_cndmask_b32_e64 v240, v158, v240, s[88:89]
	v_cndmask_b32_e64 v241, v158, v241, s[90:91]
	v_cndmask_b32_e64 v242, v158, v242, s[92:93]
	v_cndmask_b32_e64 v243, v158, v243, s[4:5]
	v_max3_f32 v151, v232, s18, v233
	v_max3_f32 v151, v151, v234, v235
	v_max3_f32 v151, v151, v236, v237
	v_max3_f32 v151, v151, v238, v239
	v_max3_f32 v151, v151, v240, v241
	v_max3_f32 v151, v151, v242, v243
	v_mov_b32_e32 v152, v150
	v_mov_b32_e32 v153, v151
	s_nop 0
	v_permlane16_swap_b32_e32 v152, v150
	v_permlane16_swap_b32_e32 v153, v151
	v_max_f32_e32 v150, v150, v152
	v_max_f32_e32 v151, v151, v153
	v_mov_b32_e32 v152, v150
	v_mov_b32_e32 v153, v151
	s_nop 0
	v_permlane32_swap_b32_e32 v152, v150
	v_permlane32_swap_b32_e32 v153, v151
	v_max_f32_e32 v150, v150, v152
	v_max_f32_e32 v151, v151, v153
	v_add_f32_e32 v110, 0x41000000, v144
	v_cmp_gt_f32_e32 vcc, v150, v110
	s_cbranch_vccz .Lna_l0_keep0
	v_max_f32_e32 v244, v144, v150
	v_sub_f32_e32 v110, v144, v244
	v_exp_f32_e32 v110, v110
	v_mov_b32_e32 v144, v244
	v_mul_f32_e32 v140, v140, v110
	v_pk_mul_f32 v[18:19], v[18:19], v[110:111] op_sel_hi:[1,0]
	v_pk_mul_f32 v[20:21], v[20:21], v[110:111] op_sel_hi:[1,0]
	v_pk_mul_f32 v[22:23], v[22:23], v[110:111] op_sel_hi:[1,0]
	v_pk_mul_f32 v[24:25], v[24:25], v[110:111] op_sel_hi:[1,0]
	v_pk_mul_f32 v[10:11], v[10:11], v[110:111] op_sel_hi:[1,0]
	v_pk_mul_f32 v[12:13], v[12:13], v[110:111] op_sel_hi:[1,0]
	v_pk_mul_f32 v[2:3], v[2:3], v[110:111] op_sel_hi:[1,0]
	v_pk_mul_f32 v[4:5], v[4:5], v[110:111] op_sel_hi:[1,0]

.Lna_l0_keep1:
	s_waitcnt lgkmcnt(6)
	ds_read_b64_tr_b16 v[180:181], v160 offset:18496
	ds_read_b64_tr_b16 v[182:183], v160 offset:20800
	ds_read_b64_tr_b16 v[184:185], v160 offset:18528
	ds_read_b64_tr_b16 v[186:187], v160 offset:20832
	ds_read_b64_tr_b16 v[154:155], v160 offset:23104
	ds_read_b64_tr_b16 v[156:157], v160 offset:25408
	ds_read_b64_tr_b16 v[200:201], v160 offset:23136
	ds_read_b64_tr_b16 v[202:203], v160 offset:25440
	v_sub_f32_e32 v224, v224, v144
	v_sub_f32_e32 v225, v225, v144
	v_exp_f32_e32 v224, v224
	v_sub_f32_e32 v226, v226, v144
	v_exp_f32_e32 v225, v225
	v_sub_f32_e32 v227, v227, v144
	v_exp_f32_e32 v226, v226
	v_exp_f32_e32 v227, v227
	v_sub_f32_e32 v228, v228, v144
	v_sub_f32_e32 v229, v229, v144
	v_exp_f32_e32 v228, v228
	v_sub_f32_e32 v230, v230, v144
	v_exp_f32_e32 v229, v229
	v_sub_f32_e32 v231, v231, v144
	v_exp_f32_e32 v230, v230
	v_exp_f32_e32 v231, v231
	v_add_f32_e32 v246, 0, v224
	v_add_f32_e32 v246, v225, v246
	v_add_f32_e32 v246, v226, v246
	v_add_f32_e32 v246, v227, v246
	v_cvt_pk_bf16_f32 v66, v224, v225
	v_cvt_pk_bf16_f32 v67, v226, v227
	v_add_f32_e32 v246, v228, v246
	v_add_f32_e32 v246, v229, v246
	v_add_f32_e32 v246, v230, v246
	v_add_f32_e32 v246, v231, v246
	v_cvt_pk_bf16_f32 v68, v228, v229
	v_cvt_pk_bf16_f32 v69, v230, v231
	v_add_f32_e32 v140, v140, v246
	s_nop 0
	v_mfma_f32_16x16x32_bf16 v[18:21], v[164:167], v[66:69], v[18:21]
	v_sub_f32_e32 v232, v232, v142
	v_sub_f32_e32 v233, v233, v142
	v_exp_f32_e32 v232, v232
	v_sub_f32_e32 v234, v234, v142
	v_exp_f32_e32 v233, v233
	v_sub_f32_e32 v235, v235, v142
	v_exp_f32_e32 v234, v234
	v_exp_f32_e32 v235, v235
	v_sub_f32_e32 v236, v236, v142
	v_sub_f32_e32 v237, v237, v142
	v_exp_f32_e32 v236, v236
	v_sub_f32_e32 v238, v238, v142
	s_waitcnt lgkmcnt(12)
	v_mfma_f32_16x16x32_bf16 v[22:25], v[168:171], v[66:69], v[22:25]
	v_exp_f32_e32 v237, v237
	v_sub_f32_e32 v239, v239, v142
	v_exp_f32_e32 v238, v238
	v_exp_f32_e32 v239, v239
	v_add_f32_e32 v247, 0, v232
	v_add_f32_e32 v247, v233, v247
	v_add_f32_e32 v247, v234, v247
	v_add_f32_e32 v247, v235, v247
	v_cvt_pk_bf16_f32 v74, v232, v233
	v_cvt_pk_bf16_f32 v75, v234, v235
	v_sub_f32_e32 v240, v240, v142
	v_sub_f32_e32 v241, v241, v142
	s_waitcnt lgkmcnt(6)
	v_mfma_f32_16x16x32_bf16 v[10:13], v[180:183], v[66:69], v[10:13]
	v_exp_f32_e32 v240, v240
	v_sub_f32_e32 v242, v242, v142
	v_exp_f32_e32 v241, v241
	v_sub_f32_e32 v243, v243, v142
	v_exp_f32_e32 v242, v242
	v_exp_f32_e32 v243, v243
	v_add_f32_e32 v247, v236, v247
	v_add_f32_e32 v247, v237, v247
	v_add_f32_e32 v247, v238, v247
	v_add_f32_e32 v247, v239, v247
	v_cvt_pk_bf16_f32 v76, v236, v237
	v_cvt_pk_bf16_f32 v77, v238, v239
	s_waitcnt lgkmcnt(4)
	v_mfma_f32_16x16x32_bf16 v[2:5], v[184:187], v[66:69], v[2:5]
	v_add_f32_e32 v247, v240, v247
	v_add_f32_e32 v247, v241, v247
	v_add_f32_e32 v247, v242, v247
	v_add_f32_e32 v247, v243, v247
	v_cvt_pk_bf16_f32 v78, v240, v241
	v_cvt_pk_bf16_f32 v79, v242, v243
	v_mov_b32_e32 v80, 0
	v_mov_b32_e32 v81, 0
	v_add_f32_e32 v137, v137, v247
	v_mfma_f32_16x16x32_bf16 v[30:33], v[164:167], v[74:77], v[30:33]
	v_mfma_f32_16x16x32_bf16 v[26:29], v[168:171], v[74:77], v[26:29]
	v_mfma_f32_16x16x32_bf16 v[30:33], v[172:175], v[78:81], v[30:33]
	v_mfma_f32_16x16x32_bf16 v[26:29], v[176:179], v[78:81], v[26:29]
	v_mfma_f32_16x16x32_bf16 v[14:17], v[180:183], v[74:77], v[14:17]
	v_mfma_f32_16x16x32_bf16 v[6:9], v[184:187], v[74:77], v[6:9]
	s_waitcnt lgkmcnt(2)
	v_mfma_f32_16x16x32_bf16 v[14:17], v[154:157], v[78:81], v[14:17]
	s_waitcnt lgkmcnt(0)
	v_mfma_f32_16x16x32_bf16 v[6:9], v[200:203], v[78:81], v[6:9]
	s_branch .LBB0_337
.Lna_loc_h1:
	ds_read_b128 v[164:167], v82 offset:2304
	ds_read_b128 v[168:171], v82 offset:2368
	ds_read_b128 v[172:175], v82 offset:4608
	ds_read_b128 v[176:179], v82 offset:4672
	ds_read_b128 v[180:183], v82 offset:6912
	ds_read_b128 v[184:187], v82 offset:6976
	ds_read2_b32 v[224:225], v147 offset0:32 offset1:33
	ds_read2_b32 v[226:227], v147 offset0:34 offset1:35
	ds_read2_b32 v[228:229], v147 offset0:48 offset1:49
	ds_read2_b32 v[230:231], v147 offset0:50 offset1:51
	ds_read2_b32 v[232:233], v147 offset0:64 offset1:65
	ds_read2_b32 v[234:235], v147 offset0:66 offset1:67
	v_mov_b32_e32 v158, 0xf149f2ca
	s_waitcnt lgkmcnt(11)
	v_mfma_f32_16x16x32_bf16 v[90:93], v[164:167], v[38:41], 0
	s_waitcnt lgkmcnt(10)
	v_mfma_f32_16x16x32_bf16 v[90:93], v[168:171], v[34:37], v[90:93]
	s_waitcnt lgkmcnt(9)
	v_mfma_f32_16x16x32_bf16 v[94:97], v[172:175], v[38:41], 0
	s_waitcnt lgkmcnt(8)
	v_mfma_f32_16x16x32_bf16 v[94:97], v[176:179], v[34:37], v[94:97]
	s_waitcnt lgkmcnt(7)
	v_mfma_f32_16x16x32_bf16 v[98:101], v[180:183], v[38:41], 0
	s_waitcnt lgkmcnt(6)
	v_mfma_f32_16x16x32_bf16 v[98:101], v[184:187], v[34:37], v[98:101]
	ds_read2_b32 v[236:237], v147 offset0:32 offset1:33
	ds_read2_b32 v[238:239], v147 offset0:34 offset1:35
	ds_read2_b32 v[240:241], v147 offset0:48 offset1:49
	ds_read2_b32 v[242:243], v147 offset0:50 offset1:51
	v_mfma_f32_16x16x32_bf16 v[102:105], v[172:175], v[46:49], 0
	v_or_b32_e32 v160, s15, v135
	v_mul_u32_u24_e32 v160, 0x48, v160
	v_lshl_add_u32 v160, v160, 1, v136
	s_waitcnt lgkmcnt(4)
	v_fmac_f32_e32 v224, 0x3e38aa3b, v90
	v_fmac_f32_e32 v225, 0x3e38aa3b, v91
	v_fmac_f32_e32 v226, 0x3e38aa3b, v92
	v_fmac_f32_e32 v227, 0x3e38aa3b, v93
	v_fmac_f32_e32 v228, 0x3e38aa3b, v94
	v_fmac_f32_e32 v229, 0x3e38aa3b, v95
	v_mfma_f32_16x16x32_bf16 v[102:105], v[176:179], v[42:45], v[102:105]
	v_fmac_f32_e32 v230, 0x3e38aa3b, v96
	v_fmac_f32_e32 v231, 0x3e38aa3b, v97
	v_fmac_f32_e32 v232, 0x3e38aa3b, v98
	v_fmac_f32_e32 v233, 0x3e38aa3b, v99
	v_fmac_f32_e32 v234, 0x3e38aa3b, v100
	v_fmac_f32_e32 v235, 0x3e38aa3b, v101
	v_cndmask_b32_e64 v224, v158, v224, s[48:49]
	v_cndmask_b32_e64 v225, v158, v225, s[50:51]
	v_cndmask_b32_e64 v226, v158, v226, s[52:53]
	v_mfma_f32_16x16x32_bf16 v[106:109], v[180:183], v[46:49], 0
	v_cndmask_b32_e64 v227, v158, v227, s[54:55]
	v_cndmask_b32_e64 v228, v158, v228, s[56:57]
	v_cndmask_b32_e64 v229, v158, v229, s[58:59]
	v_cndmask_b32_e64 v230, v158, v230, s[60:61]
	v_cndmask_b32_e64 v231, v158, v231, s[62:63]
	v_cndmask_b32_e64 v232, v158, v232, s[64:65]
	v_cndmask_b32_e64 v233, v158, v233, s[66:67]
	v_cndmask_b32_e64 v234, v158, v234, s[68:69]
	v_cndmask_b32_e64 v235, v158, v235, s[70:71]
	v_mfma_f32_16x16x32_bf16 v[106:109], v[184:187], v[42:45], v[106:109]
	v_max3_f32 v150, v224, s18, v225
	v_max3_f32 v150, v150, v226, v227
	v_max3_f32 v150, v150, v228, v229
	v_max3_f32 v150, v150, v230, v231
	v_max3_f32 v150, v150, v232, v233
	v_max3_f32 v150, v150, v234, v235
	s_waitcnt lgkmcnt(0)
	ds_read_b64_tr_b16 v[164:165], v160 offset:18432
	ds_read_b64_tr_b16 v[166:167], v160 offset:20736
	ds_read_b64_tr_b16 v[168:169], v160 offset:18464
	ds_read_b64_tr_b16 v[170:171], v160 offset:20768
	ds_read_b64_tr_b16 v[172:173], v160 offset:23040
	ds_read_b64_tr_b16 v[174:175], v160 offset:25344
	ds_read_b64_tr_b16 v[176:177], v160 offset:23072
	ds_read_b64_tr_b16 v[178:179], v160 offset:25376
	v_fmac_f32_e32 v236, 0x3e38aa3b, v102
	v_fmac_f32_e32 v237, 0x3e38aa3b, v103
	v_fmac_f32_e32 v238, 0x3e38aa3b, v104
	v_fmac_f32_e32 v239, 0x3e38aa3b, v105
	v_fmac_f32_e32 v240, 0x3e38aa3b, v106
	v_fmac_f32_e32 v241, 0x3e38aa3b, v107
	v_fmac_f32_e32 v242, 0x3e38aa3b, v108
	v_fmac_f32_e32 v243, 0x3e38aa3b, v109
	v_cndmask_b32_e64 v236, v158, v236, s[88:89]
	v_cndmask_b32_e64 v237, v158, v237, s[90:91]
	v_cndmask_b32_e64 v238, v158, v238, s[92:93]
	v_cndmask_b32_e64 v239, v158, v239, s[4:5]
	v_cndmask_b32_e64 v240, v158, v240, s[94:95]
	v_cndmask_b32_e64 v241, v158, v241, s[6:7]
	v_cndmask_b32_e64 v242, v158, v242, s[8:9]
	v_cndmask_b32_e64 v243, v158, v243, s[96:97]
	v_max3_f32 v151, v236, s18, v237
	v_max3_f32 v151, v151, v238, v239
	v_max3_f32 v151, v151, v240, v241
	v_max3_f32 v151, v151, v242, v243
	v_mov_b32_e32 v152, v150
	v_mov_b32_e32 v153, v151
	s_nop 0
	v_permlane16_swap_b32_e32 v152, v150
	v_permlane16_swap_b32_e32 v153, v151
	v_max_f32_e32 v150, v150, v152
	v_max_f32_e32 v151, v151, v153
	v_mov_b32_e32 v152, v150
	v_mov_b32_e32 v153, v151
	s_nop 0
	v_permlane32_swap_b32_e32 v152, v150
	v_permlane32_swap_b32_e32 v153, v151
	v_max_f32_e32 v150, v150, v152
	v_max_f32_e32 v151, v151, v153
	v_add_f32_e32 v110, 0x41000000, v144
	v_cmp_gt_f32_e32 vcc, v150, v110
	s_cbranch_vccz .Lna_l1_keep0
	v_max_f32_e32 v244, v144, v150
	v_sub_f32_e32 v110, v144, v244
	v_exp_f32_e32 v110, v110
	v_mov_b32_e32 v144, v244
	v_mul_f32_e32 v140, v140, v110
	v_pk_mul_f32 v[18:19], v[18:19], v[110:111] op_sel_hi:[1,0]
	v_pk_mul_f32 v[20:21], v[20:21], v[110:111] op_sel_hi:[1,0]
	v_pk_mul_f32 v[22:23], v[22:23], v[110:111] op_sel_hi:[1,0]
	v_pk_mul_f32 v[24:25], v[24:25], v[110:111] op_sel_hi:[1,0]
	v_pk_mul_f32 v[10:11], v[10:11], v[110:111] op_sel_hi:[1,0]
	v_pk_mul_f32 v[12:13], v[12:13], v[110:111] op_sel_hi:[1,0]
	v_pk_mul_f32 v[2:3], v[2:3], v[110:111] op_sel_hi:[1,0]
	v_pk_mul_f32 v[4:5], v[4:5], v[110:111] op_sel_hi:[1,0]

.Lna_l1_keep1:
	s_waitcnt lgkmcnt(6)
	ds_read_b64_tr_b16 v[180:181], v160 offset:18496
	ds_read_b64_tr_b16 v[182:183], v160 offset:20800
	ds_read_b64_tr_b16 v[184:185], v160 offset:18528
	ds_read_b64_tr_b16 v[186:187], v160 offset:20832
	ds_read_b64_tr_b16 v[154:155], v160 offset:23104
	ds_read_b64_tr_b16 v[156:157], v160 offset:25408
	ds_read_b64_tr_b16 v[200:201], v160 offset:23136
	ds_read_b64_tr_b16 v[202:203], v160 offset:25440
	v_sub_f32_e32 v224, v224, v144
	v_sub_f32_e32 v225, v225, v144
	v_exp_f32_e32 v224, v224
	v_sub_f32_e32 v226, v226, v144
	v_exp_f32_e32 v225, v225
	v_sub_f32_e32 v227, v227, v144
	v_exp_f32_e32 v226, v226
	v_exp_f32_e32 v227, v227
	v_mov_b32_e32 v66, 0
	v_mov_b32_e32 v67, 0
	v_sub_f32_e32 v228, v228, v144
	v_sub_f32_e32 v229, v229, v144
	v_exp_f32_e32 v228, v228
	v_sub_f32_e32 v230, v230, v144
	v_exp_f32_e32 v229, v229
	v_sub_f32_e32 v231, v231, v144
	v_exp_f32_e32 v230, v230
	v_exp_f32_e32 v231, v231
	v_add_f32_e32 v246, 0, v224
	v_add_f32_e32 v246, v225, v246
	v_add_f32_e32 v246, v226, v246
	v_add_f32_e32 v246, v227, v246
	v_cvt_pk_bf16_f32 v68, v224, v225
	v_cvt_pk_bf16_f32 v69, v226, v227
	v_sub_f32_e32 v232, v232, v144
	v_sub_f32_e32 v233, v233, v144
	v_exp_f32_e32 v232, v232
	v_sub_f32_e32 v234, v234, v144
	v_exp_f32_e32 v233, v233
	v_sub_f32_e32 v235, v235, v144
	v_exp_f32_e32 v234, v234
	v_exp_f32_e32 v235, v235
	v_add_f32_e32 v246, v228, v246
	v_add_f32_e32 v246, v229, v246
	v_add_f32_e32 v246, v230, v246
	v_add_f32_e32 v246, v231, v246
	v_cvt_pk_bf16_f32 v70, v228, v229
	v_cvt_pk_bf16_f32 v71, v230, v231
	v_add_f32_e32 v246, v232, v246
	v_add_f32_e32 v246, v233, v246
	v_add_f32_e32 v246, v234, v246
	v_add_f32_e32 v246, v235, v246
	v_cvt_pk_bf16_f32 v72, v232, v233
	v_cvt_pk_bf16_f32 v73, v234, v235
	v_add_f32_e32 v140, v140, v246
	v_mfma_f32_16x16x32_bf16 v[18:21], v[164:167], v[66:69], v[18:21]
	v_sub_f32_e32 v236, v236, v142
	v_sub_f32_e32 v237, v237, v142
	v_exp_f32_e32 v236, v236
	v_sub_f32_e32 v238, v238, v142
	s_waitcnt lgkmcnt(12)
	v_mfma_f32_16x16x32_bf16 v[22:25], v[168:171], v[66:69], v[22:25]
	v_exp_f32_e32 v237, v237
	v_sub_f32_e32 v239, v239, v142
	v_exp_f32_e32 v238, v238
	v_exp_f32_e32 v239, v239
	s_waitcnt lgkmcnt(10)
	v_mfma_f32_16x16x32_bf16 v[18:21], v[172:175], v[70:73], v[18:21]
	v_sub_f32_e32 v240, v240, v142
	v_sub_f32_e32 v241, v241, v142
	v_exp_f32_e32 v240, v240
	v_sub_f32_e32 v242, v242, v142
	s_waitcnt lgkmcnt(8)
	v_mfma_f32_16x16x32_bf16 v[22:25], v[176:179], v[70:73], v[22:25]
	v_exp_f32_e32 v241, v241
	v_sub_f32_e32 v243, v243, v142
	v_exp_f32_e32 v242, v242
	v_exp_f32_e32 v243, v243
	s_waitcnt lgkmcnt(6)
	v_mfma_f32_16x16x32_bf16 v[10:13], v[180:183], v[66:69], v[10:13]
	v_add_f32_e32 v247, 0, v236
	v_add_f32_e32 v247, v237, v247
	v_add_f32_e32 v247, v238, v247
	v_add_f32_e32 v247, v239, v247
	s_waitcnt lgkmcnt(4)
	v_mfma_f32_16x16x32_bf16 v[2:5], v[184:187], v[66:69], v[2:5]
	v_cvt_pk_bf16_f32 v78, v236, v237
	v_cvt_pk_bf16_f32 v79, v238, v239
	v_add_f32_e32 v247, v240, v247
	v_add_f32_e32 v247, v241, v247
	s_waitcnt lgkmcnt(2)
	v_mfma_f32_16x16x32_bf16 v[10:13], v[154:157], v[70:73], v[10:13]
	v_add_f32_e32 v247, v242, v247
	v_add_f32_e32 v247, v243, v247
	v_cvt_pk_bf16_f32 v80, v240, v241
	v_cvt_pk_bf16_f32 v81, v242, v243
	s_waitcnt lgkmcnt(0)
	v_mfma_f32_16x16x32_bf16 v[2:5], v[200:203], v[70:73], v[2:5]
	v_add_f32_e32 v137, v137, v247
	v_mfma_f32_16x16x32_bf16 v[30:33], v[172:175], v[78:81], v[30:33]
	v_mfma_f32_16x16x32_bf16 v[26:29], v[176:179], v[78:81], v[26:29]
	v_mfma_f32_16x16x32_bf16 v[14:17], v[154:157], v[78:81], v[14:17]
	v_mfma_f32_16x16x32_bf16 v[6:9], v[200:203], v[78:81], v[6:9]
	s_branch .LBB0_337
